# handoff priority edit + up phase pn order reversed + down phase round order transposed (ACT streamed once)
# speedup vs baseline: 1.0106x; 1.0085x over previous
.LBB0_225:
	s_ashr_i32 s0, s3, 3
	s_add_i32 s0, s13, s0
	s_ashr_i32 s1, s0, 31
	s_lshr_b32 s1, s1, 26
	s_add_i32 s1, s0, s1
	s_ashr_i32 s3, s1, 6
	s_and_b32 s1, s1, 0xffc0
	s_sub_i32 s0, s0, s1
	s_bfe_i32 s1, s0, 0x80000
	s_bfe_u32 s1, s1, 0x3000c
	s_add_i32 s1, s0, s1
	s_bfe_i32 s10, s1, 0x80000
	s_and_b32 s1, s1, 0xf8
	s_sub_i32 s0, s0, s1
	s_lshl_b32 s3, s3, 3
	s_sext_i32_i16 s10, s10
	s_sext_i32_i8 s0, s0
	s_add_i32 s48, s3, s0
	s_ashr_i32 s47, s10, 3
	s_add_i32 s48, s3, s47
	s_mov_b32 s47, s0

.LBB0_237:
	s_ashr_i32 s0, s18, 3
	s_add_i32 s0, s24, s0
	s_ashr_i32 s1, s0, 31
	s_lshr_b32 s1, s1, 26
	s_add_i32 s1, s0, s1
	s_ashr_i32 s4, s1, 6
	s_lshl_b32 s4, s4, 3
	s_sub_i32 s5, 64, s4
	s_min_i32 s5, s5, 8
	s_abs_i32 s18, s5
	v_cvt_f32_u32_e32 v2, s18
	s_sub_i32 s24, 0, s18
	s_andn2_b32 s1, s1, 63
	s_sub_i32 s0, s0, s1
	v_rcp_iflag_f32_e32 v2, v2
	s_abs_i32 s1, s0
	s_xor_b32 s19, s0, s5
	s_ashr_i32 s19, s19, 31
	v_mul_f32_e32 v2, 0x4f7ffffe, v2
	v_cvt_u32_f32_e32 v2, v2
	s_nop 0
	v_readfirstlane_b32 s25, v2
	s_mul_i32 s24, s24, s25
	s_mul_hi_u32 s24, s25, s24
	s_add_i32 s25, s25, s24
	s_mul_hi_u32 s24, s1, s25
	s_mul_i32 s25, s24, s18
	s_sub_i32 s1, s1, s25
	s_add_i32 s26, s24, 1
	s_sub_i32 s25, s1, s18
	s_cmp_ge_u32 s1, s18
	s_cselect_b32 s24, s26, s24
	s_cselect_b32 s1, s25, s1
	s_add_i32 s25, s24, 1
	s_cmp_ge_u32 s1, s18
	s_cselect_b32 s1, s25, s24
	s_xor_b32 s1, s1, s19
	s_sub_i32 s45, s1, s19
	s_mul_i32 s1, s45, s5
	s_sub_i32 s0, s0, s1
	s_add_i32 s46, s4, s0
	s_add_i32 s46, s4, s45
	s_mov_b32 s45, s0
